# GEMM epilogue stores of act / PROJ / Q / KV marked sc1 (write-through): the grid barriers' L2 write-back has less to flush
# speedup vs baseline: 1.0060x; 1.0060x over previous
.LBB0_242:
	s_andn2_b64 vcc, exec, s[6:7]
	s_cbranch_vccnz .LBB0_244
	s_waitcnt lgkmcnt(0)
	v_add_u32_e32 v144, s8, v155
	v_lshlrev_b32_e32 v146, 1, v144
	v_ashrrev_i32_e32 v147, 31, v146
	v_lshl_add_u64 v[146:147], v[146:147], 2, s[60:61]
	global_load_dword v202, v[146:147], off offset:4
	global_load_dword v203, v[146:147], off offset:132
	global_load_dword v204, v[146:147], off offset:260
	global_load_dword v205, v[146:147], off offset:388
	global_load_dword v206, v[146:147], off offset:1028
	global_load_dword v207, v[146:147], off offset:1156
	global_load_dword v208, v[146:147], off offset:1284
	global_load_dword v209, v[146:147], off offset:1412
	s_lshl_b32 s6, s46, 7
	v_ashrrev_i32_e32 v145, 31, v144
	v_readlane_b32 s36, v255, 1
	s_ashr_i32 s7, s6, 31
	v_readlane_b32 s37, v255, 2
	s_lshl_b64 s[6:7], s[6:7], 1
	s_waitcnt vmcnt(0)
	v_fmamk_f32 v0, v202, 0x3b800000, v139
	v_rsq_f32_e32 v150, v0
	v_lshlrev_b32_e32 v0, 1, v138
	v_pk_mul_f32 v[148:149], v[128:129], v[150:151] op_sel_hi:[1,0]
	v_pk_mul_f32 v[146:147], v[126:127], v[150:151] op_sel_hi:[1,0]
	v_pk_mul_f32 v[160:161], v[124:125], v[150:151] op_sel_hi:[1,0]
	v_pk_mul_f32 v[162:163], v[122:123], v[150:151] op_sel_hi:[1,0]
	v_cvt_pk_bf16_f32 v146, v146, v147
	v_cvt_pk_bf16_f32 v147, v148, v149
	s_nop 0
	v_cvt_pk_bf16_f32 v148, v162, v163
	v_cvt_pk_bf16_f32 v149, v160, v161
	v_lshlrev_b64 v[160:161], 10, v[144:145]
	v_lshl_add_u64 v[160:161], s[36:37], 0, v[160:161]
	v_lshl_add_u64 v[160:161], v[160:161], 0, s[6:7]
	v_lshrrev_b32_e32 v145, 21, v145
	v_lshl_add_u64 v[160:161], v[160:161], 0, v[0:1]
	v_add_u32_e32 v159, v144, v145
	global_store_dwordx4 v[160:161], v[146:149], off sc1
	v_pk_mul_f32 v[160:161], v[116:117], v[150:151] op_sel_hi:[1,0]
	v_ashrrev_i32_e32 v159, 11, v159
	v_pk_mul_f32 v[148:149], v[120:121], v[150:151] op_sel_hi:[1,0]
	v_pk_mul_f32 v[146:147], v[118:119], v[150:151] op_sel_hi:[1,0]
	v_pk_mul_f32 v[150:151], v[114:115], v[150:151] op_sel_hi:[1,0]
	v_mul_i32_i24_e32 v162, 0x800, v159
	v_cvt_pk_bf16_f32 v146, v146, v147
	v_cvt_pk_bf16_f32 v147, v148, v149
	v_cvt_pk_bf16_f32 v148, v150, v151
	v_lshl_add_u32 v150, v159, 2, s46
	v_sub_u32_e32 v162, v144, v162
	v_ashrrev_i32_e32 v151, 31, v150
	v_ashrrev_i32_e32 v163, 31, v162
	v_lshlrev_b64 v[150:151], 19, v[150:151]
	v_cvt_pk_bf16_f32 v149, v160, v161
	v_lshl_add_u64 v[150:151], s[96:97], 0, v[150:151]
	v_lshlrev_b64 v[160:161], 8, v[162:163]
	v_lshl_add_u64 v[150:151], v[150:151], 0, v[160:161]
	v_lshl_add_u64 v[150:151], v[150:151], 0, v[0:1]
	global_store_dwordx4 v[150:151], v[146:149], off sc1
	v_or_b32_e32 v150, 16, v144
	v_ashrrev_i32_e32 v151, 31, v150
	v_lshlrev_b32_e32 v146, 1, v150
	v_ashrrev_i32_e32 v147, 31, v146
	v_lshl_add_u64 v[146:147], v[146:147], 2, s[60:61]
	v_fmamk_f32 v146, v203, 0x3b800000, v139
	v_rsq_f32_e32 v160, v146
	s_nop 0
	v_pk_mul_f32 v[148:149], v[112:113], v[160:161] op_sel_hi:[1,0]
	v_pk_mul_f32 v[146:147], v[110:111], v[160:161] op_sel_hi:[1,0]
	v_pk_mul_f32 v[162:163], v[108:109], v[160:161] op_sel_hi:[1,0]
	v_pk_mul_f32 v[164:165], v[106:107], v[160:161] op_sel_hi:[1,0]
	v_cvt_pk_bf16_f32 v146, v146, v147
	v_cvt_pk_bf16_f32 v147, v148, v149
	s_nop 0
	v_cvt_pk_bf16_f32 v148, v164, v165
	v_cvt_pk_bf16_f32 v149, v162, v163
	v_lshlrev_b64 v[162:163], 10, v[150:151]
	v_lshl_add_u64 v[162:163], s[36:37], 0, v[162:163]
	v_lshl_add_u64 v[162:163], v[162:163], 0, s[6:7]
	v_lshl_add_u64 v[162:163], v[162:163], 0, v[0:1]
	v_add_u32_e32 v151, v150, v145
	global_store_dwordx4 v[162:163], v[146:149], off sc1
	v_pk_mul_f32 v[162:163], v[100:101], v[160:161] op_sel_hi:[1,0]
	v_ashrrev_i32_e32 v151, 11, v151
	v_pk_mul_f32 v[148:149], v[104:105], v[160:161] op_sel_hi:[1,0]
	v_pk_mul_f32 v[146:147], v[102:103], v[160:161] op_sel_hi:[1,0]
	v_pk_mul_f32 v[160:161], v[98:99], v[160:161] op_sel_hi:[1,0]
	v_mul_i32_i24_e32 v159, 0x800, v151
	v_cvt_pk_bf16_f32 v146, v146, v147
	v_cvt_pk_bf16_f32 v147, v148, v149
	v_cvt_pk_bf16_f32 v148, v160, v161
	v_lshl_add_u32 v160, v151, 2, s46
	v_sub_u32_e32 v150, v150, v159
	v_ashrrev_i32_e32 v161, 31, v160
	v_ashrrev_i32_e32 v151, 31, v150
	v_lshlrev_b64 v[160:161], 19, v[160:161]
	v_lshl_add_u64 v[160:161], s[96:97], 0, v[160:161]
	v_lshlrev_b64 v[150:151], 8, v[150:151]
	v_lshl_add_u64 v[150:151], v[160:161], 0, v[150:151]
	v_lshl_add_u64 v[150:151], v[150:151], 0, v[0:1]
	v_cvt_pk_bf16_f32 v149, v162, v163
	global_store_dwordx4 v[150:151], v[146:149], off sc1
	v_or_b32_e32 v150, 32, v144
	v_ashrrev_i32_e32 v151, 31, v150
	v_lshlrev_b32_e32 v146, 1, v150
	v_ashrrev_i32_e32 v147, 31, v146
	v_lshl_add_u64 v[146:147], v[146:147], 2, s[60:61]
	v_fmamk_f32 v146, v204, 0x3b800000, v139
	v_rsq_f32_e32 v160, v146
	s_nop 0
	v_pk_mul_f32 v[148:149], v[96:97], v[160:161] op_sel_hi:[1,0]
	v_pk_mul_f32 v[146:147], v[94:95], v[160:161] op_sel_hi:[1,0]
	v_pk_mul_f32 v[162:163], v[92:93], v[160:161] op_sel_hi:[1,0]
	v_pk_mul_f32 v[164:165], v[90:91], v[160:161] op_sel_hi:[1,0]
	v_cvt_pk_bf16_f32 v146, v146, v147
	v_cvt_pk_bf16_f32 v147, v148, v149
	s_nop 0
	v_cvt_pk_bf16_f32 v148, v164, v165
	v_cvt_pk_bf16_f32 v149, v162, v163
	v_lshlrev_b64 v[162:163], 10, v[150:151]
	v_lshl_add_u64 v[162:163], s[36:37], 0, v[162:163]
	v_lshl_add_u64 v[162:163], v[162:163], 0, s[6:7]
	v_lshl_add_u64 v[162:163], v[162:163], 0, v[0:1]
	v_add_u32_e32 v151, v150, v145
	global_store_dwordx4 v[162:163], v[146:149], off sc1
	v_pk_mul_f32 v[162:163], v[84:85], v[160:161] op_sel_hi:[1,0]
	v_ashrrev_i32_e32 v151, 11, v151
	v_pk_mul_f32 v[148:149], v[88:89], v[160:161] op_sel_hi:[1,0]
	v_pk_mul_f32 v[146:147], v[86:87], v[160:161] op_sel_hi:[1,0]
	v_pk_mul_f32 v[160:161], v[82:83], v[160:161] op_sel_hi:[1,0]
	v_mul_i32_i24_e32 v159, 0x800, v151
	v_cvt_pk_bf16_f32 v146, v146, v147
	v_cvt_pk_bf16_f32 v147, v148, v149
	v_cvt_pk_bf16_f32 v148, v160, v161
	v_lshl_add_u32 v160, v151, 2, s46
	v_sub_u32_e32 v150, v150, v159
	v_ashrrev_i32_e32 v161, 31, v160
	v_ashrrev_i32_e32 v151, 31, v150
	v_lshlrev_b64 v[160:161], 19, v[160:161]
	v_lshl_add_u64 v[160:161], s[96:97], 0, v[160:161]
	v_lshlrev_b64 v[150:151], 8, v[150:151]
	v_lshl_add_u64 v[150:151], v[160:161], 0, v[150:151]
	v_lshl_add_u64 v[150:151], v[150:151], 0, v[0:1]
	v_cvt_pk_bf16_f32 v149, v162, v163
	global_store_dwordx4 v[150:151], v[146:149], off sc1
	v_or_b32_e32 v150, 48, v144
	v_ashrrev_i32_e32 v151, 31, v150
	v_lshlrev_b32_e32 v146, 1, v150
	v_ashrrev_i32_e32 v147, 31, v146
	v_lshl_add_u64 v[146:147], v[146:147], 2, s[60:61]
	v_add_u32_e32 v145, v150, v145
	v_ashrrev_i32_e32 v145, 11, v145
	v_fmamk_f32 v146, v205, 0x3b800000, v139
	v_rsq_f32_e32 v160, v146
	s_nop 0
	v_pk_mul_f32 v[148:149], v[80:81], v[160:161] op_sel_hi:[1,0]
	v_pk_mul_f32 v[146:147], v[78:79], v[160:161] op_sel_hi:[1,0]
	v_pk_mul_f32 v[162:163], v[76:77], v[160:161] op_sel_hi:[1,0]
	v_pk_mul_f32 v[164:165], v[74:75], v[160:161] op_sel_hi:[1,0]
	v_cvt_pk_bf16_f32 v146, v146, v147
	v_cvt_pk_bf16_f32 v147, v148, v149
	s_nop 0
	v_cvt_pk_bf16_f32 v148, v164, v165
	v_cvt_pk_bf16_f32 v149, v162, v163
	v_lshlrev_b64 v[162:163], 10, v[150:151]
	v_lshl_add_u64 v[162:163], s[36:37], 0, v[162:163]
	v_lshl_add_u64 v[162:163], v[162:163], 0, s[6:7]
	v_lshl_add_u64 v[162:163], v[162:163], 0, v[0:1]
	global_store_dwordx4 v[162:163], v[146:149], off sc1
	v_pk_mul_f32 v[162:163], v[68:69], v[160:161] op_sel_hi:[1,0]
	v_mul_i32_i24_e32 v151, 0x800, v145
	v_pk_mul_f32 v[148:149], v[72:73], v[160:161] op_sel_hi:[1,0]
	v_pk_mul_f32 v[146:147], v[70:71], v[160:161] op_sel_hi:[1,0]
	v_pk_mul_f32 v[160:161], v[66:67], v[160:161] op_sel_hi:[1,0]
	v_cvt_pk_bf16_f32 v146, v146, v147
	v_cvt_pk_bf16_f32 v147, v148, v149
	v_sub_u32_e32 v150, v150, v151
	v_cvt_pk_bf16_f32 v148, v160, v161
	v_lshl_add_u32 v160, v145, 2, s46
	v_ashrrev_i32_e32 v161, 31, v160
	v_ashrrev_i32_e32 v151, 31, v150
	v_lshlrev_b64 v[160:161], 19, v[160:161]
	v_lshl_add_u64 v[160:161], s[96:97], 0, v[160:161]
	v_lshlrev_b64 v[150:151], 8, v[150:151]
	v_lshl_add_u64 v[150:151], v[160:161], 0, v[150:151]
	v_lshl_add_u64 v[150:151], v[150:151], 0, v[0:1]
	v_cvt_pk_bf16_f32 v149, v162, v163
	global_store_dwordx4 v[150:151], v[146:149], off sc1
	v_add_u32_e32 v150, 0x80, v144
	v_ashrrev_i32_e32 v151, 31, v150
	v_lshlrev_b32_e32 v146, 1, v150
	v_ashrrev_i32_e32 v147, 31, v146
	v_lshl_add_u64 v[146:147], v[146:147], 2, s[60:61]
	v_fmamk_f32 v145, v206, 0x3b800000, v139
	v_rsq_f32_e32 v160, v145
	v_lshrrev_b32_e32 v145, 21, v151
	v_add_u32_e32 v145, v150, v145
	v_ashrrev_i32_e32 v145, 11, v145
	v_pk_mul_f32 v[148:149], v[64:65], v[160:161] op_sel_hi:[1,0]
	v_pk_mul_f32 v[146:147], v[62:63], v[160:161] op_sel_hi:[1,0]
	v_pk_mul_f32 v[162:163], v[60:61], v[160:161] op_sel_hi:[1,0]
	v_pk_mul_f32 v[164:165], v[58:59], v[160:161] op_sel_hi:[1,0]
	v_cvt_pk_bf16_f32 v146, v146, v147
	v_cvt_pk_bf16_f32 v147, v148, v149
	s_nop 0
	v_cvt_pk_bf16_f32 v148, v164, v165
	v_cvt_pk_bf16_f32 v149, v162, v163
	v_lshlrev_b64 v[162:163], 10, v[150:151]
	v_lshl_add_u64 v[162:163], s[36:37], 0, v[162:163]
	v_lshl_add_u64 v[162:163], v[162:163], 0, s[6:7]
	v_lshl_add_u64 v[162:163], v[162:163], 0, v[0:1]
	global_store_dwordx4 v[162:163], v[146:149], off sc1
	v_pk_mul_f32 v[162:163], v[52:53], v[160:161] op_sel_hi:[1,0]
	v_mul_i32_i24_e32 v151, 0x800, v145
	v_pk_mul_f32 v[148:149], v[56:57], v[160:161] op_sel_hi:[1,0]
	v_pk_mul_f32 v[146:147], v[54:55], v[160:161] op_sel_hi:[1,0]
	v_pk_mul_f32 v[160:161], v[50:51], v[160:161] op_sel_hi:[1,0]
	v_cvt_pk_bf16_f32 v146, v146, v147
	v_cvt_pk_bf16_f32 v147, v148, v149
	v_sub_u32_e32 v150, v150, v151
	v_cvt_pk_bf16_f32 v148, v160, v161
	v_lshl_add_u32 v160, v145, 2, s46
	v_ashrrev_i32_e32 v161, 31, v160
	v_ashrrev_i32_e32 v151, 31, v150
	v_lshlrev_b64 v[160:161], 19, v[160:161]
	v_lshl_add_u64 v[160:161], s[96:97], 0, v[160:161]
	v_lshlrev_b64 v[150:151], 8, v[150:151]
	v_lshl_add_u64 v[150:151], v[160:161], 0, v[150:151]
	v_lshl_add_u64 v[150:151], v[150:151], 0, v[0:1]
	v_cvt_pk_bf16_f32 v149, v162, v163
	global_store_dwordx4 v[150:151], v[146:149], off sc1
	v_add_u32_e32 v150, 0x90, v144
	v_ashrrev_i32_e32 v151, 31, v150
	v_lshlrev_b32_e32 v146, 1, v150
	v_ashrrev_i32_e32 v147, 31, v146
	v_lshl_add_u64 v[146:147], v[146:147], 2, s[60:61]
	v_fmamk_f32 v145, v207, 0x3b800000, v139
	v_rsq_f32_e32 v160, v145
	v_lshrrev_b32_e32 v145, 21, v151
	v_add_u32_e32 v145, v150, v145
	v_ashrrev_i32_e32 v145, 11, v145
	v_pk_mul_f32 v[148:149], v[48:49], v[160:161] op_sel_hi:[1,0]
	v_pk_mul_f32 v[146:147], v[46:47], v[160:161] op_sel_hi:[1,0]
	v_pk_mul_f32 v[162:163], v[44:45], v[160:161] op_sel_hi:[1,0]
	v_pk_mul_f32 v[164:165], v[42:43], v[160:161] op_sel_hi:[1,0]
	v_cvt_pk_bf16_f32 v146, v146, v147
	v_cvt_pk_bf16_f32 v147, v148, v149
	s_nop 0
	v_cvt_pk_bf16_f32 v148, v164, v165
	v_cvt_pk_bf16_f32 v149, v162, v163
	v_lshlrev_b64 v[162:163], 10, v[150:151]
	v_lshl_add_u64 v[162:163], s[36:37], 0, v[162:163]
	v_lshl_add_u64 v[162:163], v[162:163], 0, s[6:7]
	v_lshl_add_u64 v[162:163], v[162:163], 0, v[0:1]
	global_store_dwordx4 v[162:163], v[146:149], off sc1
	v_pk_mul_f32 v[162:163], v[36:37], v[160:161] op_sel_hi:[1,0]
	v_mul_i32_i24_e32 v151, 0x800, v145
	v_pk_mul_f32 v[148:149], v[40:41], v[160:161] op_sel_hi:[1,0]
	v_pk_mul_f32 v[146:147], v[38:39], v[160:161] op_sel_hi:[1,0]
	v_pk_mul_f32 v[160:161], v[34:35], v[160:161] op_sel_hi:[1,0]
	v_cvt_pk_bf16_f32 v146, v146, v147
	v_cvt_pk_bf16_f32 v147, v148, v149
	v_sub_u32_e32 v150, v150, v151
	v_cvt_pk_bf16_f32 v148, v160, v161
	v_lshl_add_u32 v160, v145, 2, s46
	v_ashrrev_i32_e32 v161, 31, v160
	v_ashrrev_i32_e32 v151, 31, v150
	v_lshlrev_b64 v[160:161], 19, v[160:161]
	v_lshl_add_u64 v[160:161], s[96:97], 0, v[160:161]
	v_lshlrev_b64 v[150:151], 8, v[150:151]
	v_lshl_add_u64 v[150:151], v[160:161], 0, v[150:151]
	v_lshl_add_u64 v[150:151], v[150:151], 0, v[0:1]
	v_cvt_pk_bf16_f32 v149, v162, v163
	global_store_dwordx4 v[150:151], v[146:149], off sc1
	v_add_u32_e32 v150, 0xa0, v144
	v_ashrrev_i32_e32 v151, 31, v150
	v_lshlrev_b32_e32 v146, 1, v150
	v_ashrrev_i32_e32 v147, 31, v146
	v_lshl_add_u64 v[146:147], v[146:147], 2, s[60:61]
	v_add_u32_e32 v144, 0xb0, v144
	v_fmamk_f32 v145, v208, 0x3b800000, v139
	v_rsq_f32_e32 v160, v145
	v_lshrrev_b32_e32 v145, 21, v151
	v_add_u32_e32 v145, v150, v145
	v_ashrrev_i32_e32 v145, 11, v145
	v_pk_mul_f32 v[148:149], v[32:33], v[160:161] op_sel_hi:[1,0]
	v_pk_mul_f32 v[146:147], v[30:31], v[160:161] op_sel_hi:[1,0]
	v_pk_mul_f32 v[162:163], v[28:29], v[160:161] op_sel_hi:[1,0]
	v_pk_mul_f32 v[164:165], v[26:27], v[160:161] op_sel_hi:[1,0]
	v_cvt_pk_bf16_f32 v146, v146, v147
	v_cvt_pk_bf16_f32 v147, v148, v149
	s_nop 0
	v_cvt_pk_bf16_f32 v148, v164, v165
	v_cvt_pk_bf16_f32 v149, v162, v163
	v_lshlrev_b64 v[162:163], 10, v[150:151]
	v_lshl_add_u64 v[162:163], s[36:37], 0, v[162:163]
	v_lshl_add_u64 v[162:163], v[162:163], 0, s[6:7]
	v_lshl_add_u64 v[162:163], v[162:163], 0, v[0:1]
	global_store_dwordx4 v[162:163], v[146:149], off sc1
	v_pk_mul_f32 v[162:163], v[20:21], v[160:161] op_sel_hi:[1,0]
	v_mul_i32_i24_e32 v151, 0x800, v145
	v_pk_mul_f32 v[148:149], v[24:25], v[160:161] op_sel_hi:[1,0]
	v_pk_mul_f32 v[146:147], v[22:23], v[160:161] op_sel_hi:[1,0]
	v_pk_mul_f32 v[160:161], v[18:19], v[160:161] op_sel_hi:[1,0]
	v_cvt_pk_bf16_f32 v146, v146, v147
	v_cvt_pk_bf16_f32 v147, v148, v149
	v_sub_u32_e32 v150, v150, v151
	v_cvt_pk_bf16_f32 v148, v160, v161
	v_lshl_add_u32 v160, v145, 2, s46
	v_ashrrev_i32_e32 v161, 31, v160
	v_ashrrev_i32_e32 v151, 31, v150
	v_lshlrev_b64 v[160:161], 19, v[160:161]
	v_lshl_add_u64 v[160:161], s[96:97], 0, v[160:161]
	v_lshlrev_b64 v[150:151], 8, v[150:151]
	v_lshl_add_u64 v[150:151], v[160:161], 0, v[150:151]
	v_lshl_add_u64 v[150:151], v[150:151], 0, v[0:1]
	v_cvt_pk_bf16_f32 v149, v162, v163
	global_store_dwordx4 v[150:151], v[146:149], off sc1
	s_nop 1
	v_lshlrev_b32_e32 v146, 1, v144
	v_ashrrev_i32_e32 v147, 31, v146
	v_lshl_add_u64 v[146:147], v[146:147], 2, s[60:61]
	v_fmamk_f32 v145, v209, 0x3b800000, v139
	v_rsq_f32_e32 v150, v145
	v_ashrrev_i32_e32 v145, 31, v144
	v_pk_mul_f32 v[148:149], v[16:17], v[150:151] op_sel_hi:[1,0]
	v_pk_mul_f32 v[146:147], v[14:15], v[150:151] op_sel_hi:[1,0]
	v_pk_mul_f32 v[160:161], v[12:13], v[150:151] op_sel_hi:[1,0]
	v_pk_mul_f32 v[162:163], v[10:11], v[150:151] op_sel_hi:[1,0]
	v_cvt_pk_bf16_f32 v146, v146, v147
	v_cvt_pk_bf16_f32 v147, v148, v149
	s_nop 0
	v_cvt_pk_bf16_f32 v148, v162, v163
	v_cvt_pk_bf16_f32 v149, v160, v161
	v_lshlrev_b64 v[160:161], 10, v[144:145]
	v_lshl_add_u64 v[160:161], s[36:37], 0, v[160:161]
	v_lshrrev_b32_e32 v145, 21, v145
	v_lshl_add_u64 v[160:161], v[160:161], 0, s[6:7]
	v_add_u32_e32 v145, v144, v145
	v_lshl_add_u64 v[160:161], v[160:161], 0, v[0:1]
	v_ashrrev_i32_e32 v159, 11, v145
	global_store_dwordx4 v[160:161], v[146:149], off sc1
	v_mul_i32_i24_e32 v145, 0x800, v159
	v_sub_u32_e32 v162, v144, v145
	v_pk_mul_f32 v[148:149], v[6:7], v[150:151] op_sel_hi:[1,0]
	v_pk_mul_f32 v[146:147], v[8:9], v[150:151] op_sel_hi:[1,0]
	v_cvt_pk_bf16_f32 v144, v148, v149
	v_lshl_add_u32 v148, v159, 2, s46
	v_ashrrev_i32_e32 v149, 31, v148
	v_pk_mul_f32 v[160:161], v[4:5], v[150:151] op_sel_hi:[1,0]
	v_pk_mul_f32 v[150:151], v[2:3], v[150:151] op_sel_hi:[1,0]
	v_ashrrev_i32_e32 v163, 31, v162
	v_lshlrev_b64 v[148:149], 19, v[148:149]
	v_cvt_pk_bf16_f32 v145, v146, v147
	v_cvt_pk_bf16_f32 v146, v150, v151
	v_lshl_add_u64 v[148:149], s[96:97], 0, v[148:149]
	v_lshlrev_b64 v[150:151], 8, v[162:163]
	v_lshl_add_u64 v[148:149], v[148:149], 0, v[150:151]
	v_lshl_add_u64 v[148:149], v[148:149], 0, v[0:1]
	v_cvt_pk_bf16_f32 v147, v160, v161
	global_store_dwordx4 v[148:149], v[144:147], off sc1

.LBB0_245:
	s_mov_b64 s[6:7], -1
	s_cmp_gt_i32 s45, 0
	v_add_u32_e32 v146, s8, v155
	s_waitcnt lgkmcnt(0)
	v_lshl_or_b32 v144, s46, 8, v138
	s_cbranch_scc0 .LBB0_247
	v_lshlrev_b32_e32 v150, 1, v146
	v_ashrrev_i32_e32 v151, 31, v150
	v_lshl_add_u64 v[150:151], v[150:151], 2, s[60:61]
	global_load_dword v202, v[150:151], off
	global_load_dword v203, v[150:151], off offset:128
	global_load_dword v204, v[150:151], off offset:256
	global_load_dword v205, v[150:151], off offset:384
	global_load_dword v206, v[150:151], off offset:1024
	global_load_dword v207, v[150:151], off offset:1152
	global_load_dword v208, v[150:151], off offset:1280
	global_load_dword v209, v[150:151], off offset:1408
	v_readlane_b32 s6, v254, 44
	v_ashrrev_i32_e32 v145, 31, v144
	v_readlane_b32 s7, v254, 45
	s_waitcnt vmcnt(0)
	v_fmamk_f32 v0, v202, 0x3b800000, v139
	v_rsq_f32_e32 v0, v0
	v_lshl_add_u64 v[148:149], v[144:145], 1, s[6:7]
	v_mad_i64_i32 v[150:151], s[6:7], v146, s41, v[148:149]
	v_pk_mul_f32 v[162:163], v[128:129], v[0:1] op_sel_hi:[1,0]
	v_pk_mul_f32 v[160:161], v[126:127], v[0:1] op_sel_hi:[1,0]
	v_pk_mul_f32 v[164:165], v[124:125], v[0:1] op_sel_hi:[1,0]
	v_pk_mul_f32 v[166:167], v[122:123], v[0:1] op_sel_hi:[1,0]
	v_cvt_pk_bf16_f32 v160, v160, v161
	v_cvt_pk_bf16_f32 v161, v162, v163
	v_or_b32_e32 v145, 16, v146
	v_cvt_pk_bf16_f32 v162, v166, v167
	v_cvt_pk_bf16_f32 v163, v164, v165
	global_store_dwordx4 v[150:151], v[160:163], off sc1
	v_pk_mul_f32 v[164:165], v[116:117], v[0:1] op_sel_hi:[1,0]
	v_pk_mul_f32 v[166:167], v[114:115], v[0:1] op_sel_hi:[1,0]
	v_pk_mul_f32 v[162:163], v[120:121], v[0:1] op_sel_hi:[1,0]
	v_pk_mul_f32 v[160:161], v[118:119], v[0:1] op_sel_hi:[1,0]
	s_nop 0
	v_cvt_pk_bf16_f32 v160, v160, v161
	v_cvt_pk_bf16_f32 v161, v162, v163
	v_cvt_pk_bf16_f32 v162, v166, v167
	v_cvt_pk_bf16_f32 v163, v164, v165
	global_store_dwordx4 v[150:151], v[160:163], off offset:256 sc1
	v_lshlrev_b32_e32 v150, 1, v145
	v_ashrrev_i32_e32 v151, 31, v150
	v_lshl_add_u64 v[150:151], v[150:151], 2, s[60:61]
	v_mad_i64_i32 v[150:151], s[6:7], v145, s41, v[148:149]
	v_or_b32_e32 v145, 32, v146
	v_fmamk_f32 v0, v203, 0x3b800000, v139
	v_rsq_f32_e32 v0, v0
	s_nop 0
	v_pk_mul_f32 v[162:163], v[112:113], v[0:1] op_sel_hi:[1,0]
	v_pk_mul_f32 v[160:161], v[110:111], v[0:1] op_sel_hi:[1,0]
	v_pk_mul_f32 v[164:165], v[108:109], v[0:1] op_sel_hi:[1,0]
	v_pk_mul_f32 v[166:167], v[106:107], v[0:1] op_sel_hi:[1,0]
	v_cvt_pk_bf16_f32 v160, v160, v161
	v_cvt_pk_bf16_f32 v161, v162, v163
	s_nop 0
	v_cvt_pk_bf16_f32 v162, v166, v167
	v_cvt_pk_bf16_f32 v163, v164, v165
	global_store_dwordx4 v[150:151], v[160:163], off sc1
	v_pk_mul_f32 v[164:165], v[100:101], v[0:1] op_sel_hi:[1,0]
	v_pk_mul_f32 v[166:167], v[98:99], v[0:1] op_sel_hi:[1,0]
	v_pk_mul_f32 v[162:163], v[104:105], v[0:1] op_sel_hi:[1,0]
	v_pk_mul_f32 v[160:161], v[102:103], v[0:1] op_sel_hi:[1,0]
	s_nop 0
	v_cvt_pk_bf16_f32 v160, v160, v161
	v_cvt_pk_bf16_f32 v161, v162, v163
	v_cvt_pk_bf16_f32 v162, v166, v167
	v_cvt_pk_bf16_f32 v163, v164, v165
	global_store_dwordx4 v[150:151], v[160:163], off offset:256 sc1
	v_lshlrev_b32_e32 v150, 1, v145
	v_ashrrev_i32_e32 v151, 31, v150
	v_lshl_add_u64 v[150:151], v[150:151], 2, s[60:61]
	v_mad_i64_i32 v[150:151], s[6:7], v145, s41, v[148:149]
	v_or_b32_e32 v145, 48, v146
	v_fmamk_f32 v0, v204, 0x3b800000, v139
	v_rsq_f32_e32 v0, v0
	s_nop 0
	v_pk_mul_f32 v[162:163], v[96:97], v[0:1] op_sel_hi:[1,0]
	v_pk_mul_f32 v[160:161], v[94:95], v[0:1] op_sel_hi:[1,0]
	v_pk_mul_f32 v[164:165], v[92:93], v[0:1] op_sel_hi:[1,0]
	v_pk_mul_f32 v[166:167], v[90:91], v[0:1] op_sel_hi:[1,0]
	v_cvt_pk_bf16_f32 v160, v160, v161
	v_cvt_pk_bf16_f32 v161, v162, v163
	s_nop 0
	v_cvt_pk_bf16_f32 v162, v166, v167
	v_cvt_pk_bf16_f32 v163, v164, v165
	global_store_dwordx4 v[150:151], v[160:163], off sc1
	v_pk_mul_f32 v[164:165], v[84:85], v[0:1] op_sel_hi:[1,0]
	v_pk_mul_f32 v[166:167], v[82:83], v[0:1] op_sel_hi:[1,0]
	v_pk_mul_f32 v[162:163], v[88:89], v[0:1] op_sel_hi:[1,0]
	v_pk_mul_f32 v[160:161], v[86:87], v[0:1] op_sel_hi:[1,0]
	s_nop 0
	v_cvt_pk_bf16_f32 v160, v160, v161
	v_cvt_pk_bf16_f32 v161, v162, v163
	v_cvt_pk_bf16_f32 v162, v166, v167
	v_cvt_pk_bf16_f32 v163, v164, v165
	global_store_dwordx4 v[150:151], v[160:163], off offset:256 sc1
	v_lshlrev_b32_e32 v150, 1, v145
	v_ashrrev_i32_e32 v151, 31, v150
	v_lshl_add_u64 v[150:151], v[150:151], 2, s[60:61]
	v_mad_i64_i32 v[150:151], s[6:7], v145, s41, v[148:149]
	v_add_u32_e32 v145, 0x80, v146
	v_fmamk_f32 v0, v205, 0x3b800000, v139
	v_rsq_f32_e32 v0, v0
	s_nop 0
	v_pk_mul_f32 v[162:163], v[80:81], v[0:1] op_sel_hi:[1,0]
	v_pk_mul_f32 v[160:161], v[78:79], v[0:1] op_sel_hi:[1,0]
	v_pk_mul_f32 v[164:165], v[76:77], v[0:1] op_sel_hi:[1,0]
	v_pk_mul_f32 v[166:167], v[74:75], v[0:1] op_sel_hi:[1,0]
	v_cvt_pk_bf16_f32 v160, v160, v161
	v_cvt_pk_bf16_f32 v161, v162, v163
	s_nop 0
	v_cvt_pk_bf16_f32 v162, v166, v167
	v_cvt_pk_bf16_f32 v163, v164, v165
	global_store_dwordx4 v[150:151], v[160:163], off sc1
	v_pk_mul_f32 v[164:165], v[68:69], v[0:1] op_sel_hi:[1,0]
	v_pk_mul_f32 v[166:167], v[66:67], v[0:1] op_sel_hi:[1,0]
	v_pk_mul_f32 v[162:163], v[72:73], v[0:1] op_sel_hi:[1,0]
	v_pk_mul_f32 v[160:161], v[70:71], v[0:1] op_sel_hi:[1,0]
	s_nop 0
	v_cvt_pk_bf16_f32 v160, v160, v161
	v_cvt_pk_bf16_f32 v161, v162, v163
	v_cvt_pk_bf16_f32 v162, v166, v167
	v_cvt_pk_bf16_f32 v163, v164, v165
	global_store_dwordx4 v[150:151], v[160:163], off offset:256 sc1
	v_lshlrev_b32_e32 v150, 1, v145
	v_ashrrev_i32_e32 v151, 31, v150
	v_lshl_add_u64 v[150:151], v[150:151], 2, s[60:61]
	v_mad_i64_i32 v[150:151], s[6:7], v145, s41, v[148:149]
	v_add_u32_e32 v145, 0x90, v146
	v_fmamk_f32 v0, v206, 0x3b800000, v139
	v_rsq_f32_e32 v0, v0
	s_nop 0
	v_pk_mul_f32 v[162:163], v[64:65], v[0:1] op_sel_hi:[1,0]
	v_pk_mul_f32 v[160:161], v[62:63], v[0:1] op_sel_hi:[1,0]
	v_pk_mul_f32 v[164:165], v[60:61], v[0:1] op_sel_hi:[1,0]
	v_pk_mul_f32 v[166:167], v[58:59], v[0:1] op_sel_hi:[1,0]
	v_cvt_pk_bf16_f32 v160, v160, v161
	v_cvt_pk_bf16_f32 v161, v162, v163
	s_nop 0
	v_cvt_pk_bf16_f32 v162, v166, v167
	v_cvt_pk_bf16_f32 v163, v164, v165
	global_store_dwordx4 v[150:151], v[160:163], off sc1
	v_pk_mul_f32 v[164:165], v[52:53], v[0:1] op_sel_hi:[1,0]
	v_pk_mul_f32 v[166:167], v[50:51], v[0:1] op_sel_hi:[1,0]
	v_pk_mul_f32 v[162:163], v[56:57], v[0:1] op_sel_hi:[1,0]
	v_pk_mul_f32 v[160:161], v[54:55], v[0:1] op_sel_hi:[1,0]
	s_nop 0
	v_cvt_pk_bf16_f32 v160, v160, v161
	v_cvt_pk_bf16_f32 v161, v162, v163
	v_cvt_pk_bf16_f32 v162, v166, v167
	v_cvt_pk_bf16_f32 v163, v164, v165
	global_store_dwordx4 v[150:151], v[160:163], off offset:256 sc1
	v_lshlrev_b32_e32 v150, 1, v145
	v_ashrrev_i32_e32 v151, 31, v150
	v_lshl_add_u64 v[150:151], v[150:151], 2, s[60:61]
	v_mad_i64_i32 v[150:151], s[6:7], v145, s41, v[148:149]
	v_add_u32_e32 v145, 0xa0, v146
	v_fmamk_f32 v0, v207, 0x3b800000, v139
	v_rsq_f32_e32 v0, v0
	s_nop 0
	v_pk_mul_f32 v[162:163], v[48:49], v[0:1] op_sel_hi:[1,0]
	v_pk_mul_f32 v[160:161], v[46:47], v[0:1] op_sel_hi:[1,0]
	v_pk_mul_f32 v[164:165], v[44:45], v[0:1] op_sel_hi:[1,0]
	v_pk_mul_f32 v[166:167], v[42:43], v[0:1] op_sel_hi:[1,0]
	v_cvt_pk_bf16_f32 v160, v160, v161
	v_cvt_pk_bf16_f32 v161, v162, v163
	s_nop 0
	v_cvt_pk_bf16_f32 v162, v166, v167
	v_cvt_pk_bf16_f32 v163, v164, v165
	global_store_dwordx4 v[150:151], v[160:163], off sc1
	v_pk_mul_f32 v[164:165], v[36:37], v[0:1] op_sel_hi:[1,0]
	v_pk_mul_f32 v[166:167], v[34:35], v[0:1] op_sel_hi:[1,0]
	v_pk_mul_f32 v[162:163], v[40:41], v[0:1] op_sel_hi:[1,0]
	v_pk_mul_f32 v[160:161], v[38:39], v[0:1] op_sel_hi:[1,0]
	s_nop 0
	v_cvt_pk_bf16_f32 v160, v160, v161
	v_cvt_pk_bf16_f32 v161, v162, v163
	v_cvt_pk_bf16_f32 v162, v166, v167
	v_cvt_pk_bf16_f32 v163, v164, v165
	global_store_dwordx4 v[150:151], v[160:163], off offset:256 sc1
	v_lshlrev_b32_e32 v150, 1, v145
	v_ashrrev_i32_e32 v151, 31, v150
	v_lshl_add_u64 v[150:151], v[150:151], 2, s[60:61]
	v_mad_i64_i32 v[150:151], s[6:7], v145, s41, v[148:149]
	v_add_u32_e32 v145, 0xb0, v146
	v_fmamk_f32 v0, v208, 0x3b800000, v139
	v_rsq_f32_e32 v0, v0
	s_nop 0
	v_pk_mul_f32 v[162:163], v[32:33], v[0:1] op_sel_hi:[1,0]
	v_pk_mul_f32 v[160:161], v[30:31], v[0:1] op_sel_hi:[1,0]
	v_pk_mul_f32 v[164:165], v[28:29], v[0:1] op_sel_hi:[1,0]
	v_pk_mul_f32 v[166:167], v[26:27], v[0:1] op_sel_hi:[1,0]
	v_cvt_pk_bf16_f32 v160, v160, v161
	v_cvt_pk_bf16_f32 v161, v162, v163
	s_nop 0
	v_cvt_pk_bf16_f32 v162, v166, v167
	v_cvt_pk_bf16_f32 v163, v164, v165
	global_store_dwordx4 v[150:151], v[160:163], off sc1
	v_pk_mul_f32 v[164:165], v[20:21], v[0:1] op_sel_hi:[1,0]
	v_pk_mul_f32 v[166:167], v[18:19], v[0:1] op_sel_hi:[1,0]
	v_pk_mul_f32 v[162:163], v[24:25], v[0:1] op_sel_hi:[1,0]
	v_pk_mul_f32 v[160:161], v[22:23], v[0:1] op_sel_hi:[1,0]
	s_nop 0
	v_cvt_pk_bf16_f32 v160, v160, v161
	v_cvt_pk_bf16_f32 v161, v162, v163
	v_cvt_pk_bf16_f32 v162, v166, v167
	v_cvt_pk_bf16_f32 v163, v164, v165
	global_store_dwordx4 v[150:151], v[160:163], off offset:256 sc1
	v_lshlrev_b32_e32 v150, 1, v145
	v_ashrrev_i32_e32 v151, 31, v150
	v_lshl_add_u64 v[150:151], v[150:151], 2, s[60:61]
	v_mad_i64_i32 v[160:161], s[6:7], v145, s41, v[148:149]
	s_mov_b64 s[6:7], 0
	v_fmamk_f32 v0, v209, 0x3b800000, v139
	v_rsq_f32_e32 v0, v0
	s_nop 0
	v_pk_mul_f32 v[150:151], v[16:17], v[0:1] op_sel_hi:[1,0]
	v_pk_mul_f32 v[148:149], v[14:15], v[0:1] op_sel_hi:[1,0]
	v_pk_mul_f32 v[162:163], v[12:13], v[0:1] op_sel_hi:[1,0]
	v_pk_mul_f32 v[164:165], v[10:11], v[0:1] op_sel_hi:[1,0]
	v_cvt_pk_bf16_f32 v148, v148, v149
	v_cvt_pk_bf16_f32 v149, v150, v151
	s_nop 0
	v_cvt_pk_bf16_f32 v150, v164, v165
	v_cvt_pk_bf16_f32 v151, v162, v163
	global_store_dwordx4 v[160:161], v[148:151], off sc1
	v_pk_mul_f32 v[162:163], v[4:5], v[0:1] op_sel_hi:[1,0]
	v_pk_mul_f32 v[164:165], v[2:3], v[0:1] op_sel_hi:[1,0]
	v_pk_mul_f32 v[150:151], v[8:9], v[0:1] op_sel_hi:[1,0]
	v_pk_mul_f32 v[148:149], v[6:7], v[0:1] op_sel_hi:[1,0]
	s_nop 0
	v_cvt_pk_bf16_f32 v148, v148, v149
	v_cvt_pk_bf16_f32 v149, v150, v151
	v_cvt_pk_bf16_f32 v150, v164, v165
	v_cvt_pk_bf16_f32 v151, v162, v163
	global_store_dwordx4 v[160:161], v[148:151], off offset:256 sc1
.LBB0_247:
	s_andn2_b64 vcc, exec, s[6:7]
	s_cbranch_vccnz .LBB0_307
	v_mov_b64_e32 v[148:149], s[74:75]
	s_cmp_lg_u32 s46, 10
	v_mad_i64_i32 v[148:149], s[6:7], v146, s42, v[148:149]
	s_cselect_b64 s[8:9], -1, 0
	s_cmp_eq_u32 s46, 10
	v_ashrrev_i32_e32 v145, 31, v144
	s_cselect_b64 s[6:7], -1, 0
	v_ashrrev_i32_e32 v147, 31, v146
	v_lshl_add_u64 v[148:149], v[144:145], 1, v[148:149]
	s_and_b64 s[36:37], s[30:31], s[6:7]
	v_cvt_pk_bf16_f32 v160, v126, v127
	v_cvt_pk_bf16_f32 v161, v128, v129
	v_cvt_pk_bf16_f32 v162, v122, v123
	v_cvt_pk_bf16_f32 v163, v124, v125
	global_store_dwordx4 v[148:149], v[160:163], off sc1
	s_and_saveexec_b64 s[6:7], s[36:37]
	s_cbranch_execz .LBB0_250
	v_lshlrev_b64 v[150:151], 5, v[146:147]
	v_lshl_add_u64 v[150:151], s[72:73], 0, v[150:151]
	global_store_dwordx4 v[150:151], v[126:129], off sc1
	global_store_dwordx4 v[150:151], v[122:125], off offset:16 sc1
.LBB0_250:
	s_or_b64 exec, exec, s[6:7]
	v_cndmask_b32_e64 v0, 0, 1, s[8:9]
	v_cmp_ne_u32_e64 s[6:7], 1, v0
	s_andn2_b64 vcc, exec, s[8:9]
	s_cbranch_vccnz .LBB0_252
	v_cvt_pk_bf16_f32 v160, v118, v119
	v_cvt_pk_bf16_f32 v161, v120, v121
	v_cvt_pk_bf16_f32 v162, v114, v115
	v_cvt_pk_bf16_f32 v163, v116, v117
	global_store_dwordx4 v[148:149], v[160:163], off offset:256 sc1

.LBB0_256:
	s_waitcnt lgkmcnt(0)
	v_or_b32_e32 v114, 16, v146
	v_mov_b64_e32 v[116:117], s[74:75]
	v_mad_i64_i32 v[116:117], s[8:9], v114, s42, v[116:117]
	v_ashrrev_i32_e32 v115, 31, v114
	v_lshl_add_u64 v[116:117], v[144:145], 1, v[116:117]
	v_cvt_pk_bf16_f32 v118, v110, v111
	v_cvt_pk_bf16_f32 v119, v112, v113
	v_cvt_pk_bf16_f32 v120, v106, v107
	v_cvt_pk_bf16_f32 v121, v108, v109
	global_store_dwordx4 v[116:117], v[118:121], off sc1
	s_and_saveexec_b64 s[8:9], s[36:37]
	s_cbranch_execnz .LBB0_259
	s_or_b64 exec, exec, s[8:9]
	s_and_b64 vcc, exec, s[6:7]
	s_cbranch_vccz .LBB0_260

.LBB0_259:
	v_lshlrev_b64 v[118:119], 5, v[114:115]
	v_lshl_add_u64 v[118:119], s[72:73], 0, v[118:119]
	global_store_dwordx4 v[118:119], v[110:113], off sc1
	global_store_dwordx4 v[118:119], v[106:109], off offset:16 sc1
	s_or_b64 exec, exec, s[8:9]
	s_and_b64 vcc, exec, s[6:7]
	s_cbranch_vccnz .LBB0_258
.LBB0_260:
	v_cvt_pk_bf16_f32 v118, v102, v103
	v_cvt_pk_bf16_f32 v119, v104, v105
	v_cvt_pk_bf16_f32 v120, v98, v99
	v_cvt_pk_bf16_f32 v121, v100, v101
	global_store_dwordx4 v[116:117], v[118:121], off offset:256 sc1
	v_cndmask_b32_e64 v0, 0, 1, s[38:39]
	v_cmp_ne_u32_e64 s[8:9], 1, v0
	s_andn2_b64 vcc, exec, s[38:39]
	s_cbranch_vccnz .LBB0_264

.LBB0_264:
	s_waitcnt lgkmcnt(0)
	v_or_b32_e32 v98, 32, v146
	v_mov_b64_e32 v[100:101], s[74:75]
	v_mad_i64_i32 v[100:101], s[38:39], v98, s42, v[100:101]
	v_ashrrev_i32_e32 v99, 31, v98
	v_lshl_add_u64 v[100:101], v[144:145], 1, v[100:101]
	v_cvt_pk_bf16_f32 v102, v94, v95
	v_cvt_pk_bf16_f32 v103, v96, v97
	v_cvt_pk_bf16_f32 v104, v90, v91
	v_cvt_pk_bf16_f32 v105, v92, v93
	global_store_dwordx4 v[100:101], v[102:105], off sc1
	s_and_saveexec_b64 s[38:39], s[36:37]
	s_cbranch_execnz .LBB0_267
	s_or_b64 exec, exec, s[38:39]
	s_and_b64 vcc, exec, s[6:7]
	s_cbranch_vccz .LBB0_268

.LBB0_267:
	v_lshlrev_b64 v[102:103], 5, v[98:99]
	v_lshl_add_u64 v[102:103], s[72:73], 0, v[102:103]
	global_store_dwordx4 v[102:103], v[94:97], off sc1
	global_store_dwordx4 v[102:103], v[90:93], off offset:16 sc1
	s_or_b64 exec, exec, s[38:39]
	s_and_b64 vcc, exec, s[6:7]
	s_cbranch_vccnz .LBB0_266
.LBB0_268:
	v_cvt_pk_bf16_f32 v102, v86, v87
	v_cvt_pk_bf16_f32 v103, v88, v89
	v_cvt_pk_bf16_f32 v104, v82, v83
	v_cvt_pk_bf16_f32 v105, v84, v85
	global_store_dwordx4 v[100:101], v[102:105], off offset:256 sc1
	s_and_b64 vcc, exec, s[8:9]
	s_cbranch_vccnz .LBB0_272

.LBB0_272:
	s_waitcnt lgkmcnt(0)
	v_or_b32_e32 v82, 48, v146
	v_mov_b64_e32 v[84:85], s[74:75]
	v_mad_i64_i32 v[84:85], s[38:39], v82, s42, v[84:85]
	v_ashrrev_i32_e32 v83, 31, v82
	v_lshl_add_u64 v[84:85], v[144:145], 1, v[84:85]
	v_cvt_pk_bf16_f32 v86, v78, v79
	v_cvt_pk_bf16_f32 v87, v80, v81
	v_cvt_pk_bf16_f32 v88, v74, v75
	v_cvt_pk_bf16_f32 v89, v76, v77
	global_store_dwordx4 v[84:85], v[86:89], off sc1
	s_and_saveexec_b64 s[38:39], s[36:37]
	s_cbranch_execnz .LBB0_275
	s_or_b64 exec, exec, s[38:39]
	s_and_b64 vcc, exec, s[6:7]
	s_cbranch_vccz .LBB0_276

.LBB0_275:
	v_lshlrev_b64 v[86:87], 5, v[82:83]
	v_lshl_add_u64 v[86:87], s[72:73], 0, v[86:87]
	global_store_dwordx4 v[86:87], v[78:81], off sc1
	global_store_dwordx4 v[86:87], v[74:77], off offset:16 sc1
	s_or_b64 exec, exec, s[38:39]
	s_and_b64 vcc, exec, s[6:7]
	s_cbranch_vccnz .LBB0_274
.LBB0_276:
	v_cvt_pk_bf16_f32 v86, v70, v71
	v_cvt_pk_bf16_f32 v87, v72, v73
	v_cvt_pk_bf16_f32 v88, v66, v67
	v_cvt_pk_bf16_f32 v89, v68, v69
	global_store_dwordx4 v[84:85], v[86:89], off offset:256 sc1
	s_and_b64 vcc, exec, s[8:9]
	s_cbranch_vccnz .LBB0_280

.LBB0_280:
	s_waitcnt lgkmcnt(0)
	v_add_u32_e32 v66, 0x80, v146
	v_mov_b64_e32 v[68:69], s[74:75]
	v_mad_i64_i32 v[68:69], s[38:39], v66, s42, v[68:69]
	v_ashrrev_i32_e32 v67, 31, v66
	v_lshl_add_u64 v[68:69], v[144:145], 1, v[68:69]
	v_cvt_pk_bf16_f32 v70, v62, v63
	v_cvt_pk_bf16_f32 v71, v64, v65
	v_cvt_pk_bf16_f32 v72, v58, v59
	v_cvt_pk_bf16_f32 v73, v60, v61
	global_store_dwordx4 v[68:69], v[70:73], off sc1
	s_and_saveexec_b64 s[38:39], s[36:37]
	s_cbranch_execnz .LBB0_283
	s_or_b64 exec, exec, s[38:39]
	s_and_b64 vcc, exec, s[6:7]
	s_cbranch_vccz .LBB0_284

.LBB0_283:
	v_lshlrev_b64 v[70:71], 5, v[66:67]
	v_lshl_add_u64 v[70:71], s[72:73], 0, v[70:71]
	global_store_dwordx4 v[70:71], v[62:65], off sc1
	global_store_dwordx4 v[70:71], v[58:61], off offset:16 sc1
	s_or_b64 exec, exec, s[38:39]
	s_and_b64 vcc, exec, s[6:7]
	s_cbranch_vccnz .LBB0_282
.LBB0_284:
	v_cvt_pk_bf16_f32 v70, v54, v55
	v_cvt_pk_bf16_f32 v71, v56, v57
	v_cvt_pk_bf16_f32 v72, v50, v51
	v_cvt_pk_bf16_f32 v73, v52, v53
	global_store_dwordx4 v[68:69], v[70:73], off offset:256 sc1
	s_and_b64 vcc, exec, s[8:9]
	s_cbranch_vccnz .LBB0_288

.LBB0_288:
	s_waitcnt lgkmcnt(0)
	v_add_u32_e32 v50, 0x90, v146
	v_mov_b64_e32 v[52:53], s[74:75]
	v_mad_i64_i32 v[52:53], s[38:39], v50, s42, v[52:53]
	v_ashrrev_i32_e32 v51, 31, v50
	v_lshl_add_u64 v[52:53], v[144:145], 1, v[52:53]
	v_cvt_pk_bf16_f32 v54, v46, v47
	v_cvt_pk_bf16_f32 v55, v48, v49
	v_cvt_pk_bf16_f32 v56, v42, v43
	v_cvt_pk_bf16_f32 v57, v44, v45
	global_store_dwordx4 v[52:53], v[54:57], off sc1
	s_and_saveexec_b64 s[38:39], s[36:37]
	s_cbranch_execnz .LBB0_291
	s_or_b64 exec, exec, s[38:39]
	s_and_b64 vcc, exec, s[6:7]
	s_cbranch_vccz .LBB0_292

.LBB0_291:
	v_lshlrev_b64 v[54:55], 5, v[50:51]
	v_lshl_add_u64 v[54:55], s[72:73], 0, v[54:55]
	global_store_dwordx4 v[54:55], v[46:49], off sc1
	global_store_dwordx4 v[54:55], v[42:45], off offset:16 sc1
	s_or_b64 exec, exec, s[38:39]
	s_and_b64 vcc, exec, s[6:7]
	s_cbranch_vccnz .LBB0_290
.LBB0_292:
	v_cvt_pk_bf16_f32 v54, v38, v39
	v_cvt_pk_bf16_f32 v55, v40, v41
	v_cvt_pk_bf16_f32 v56, v34, v35
	v_cvt_pk_bf16_f32 v57, v36, v37
	global_store_dwordx4 v[52:53], v[54:57], off offset:256 sc1
	s_and_b64 vcc, exec, s[8:9]
	s_cbranch_vccnz .LBB0_296

.LBB0_296:
	s_waitcnt lgkmcnt(0)
	v_add_u32_e32 v34, 0xa0, v146
	v_mov_b64_e32 v[36:37], s[74:75]
	v_mad_i64_i32 v[36:37], s[38:39], v34, s42, v[36:37]
	v_ashrrev_i32_e32 v35, 31, v34
	v_lshl_add_u64 v[36:37], v[144:145], 1, v[36:37]
	v_cvt_pk_bf16_f32 v38, v30, v31
	v_cvt_pk_bf16_f32 v39, v32, v33
	v_cvt_pk_bf16_f32 v40, v26, v27
	v_cvt_pk_bf16_f32 v41, v28, v29
	global_store_dwordx4 v[36:37], v[38:41], off sc1
	s_and_saveexec_b64 s[38:39], s[36:37]
	s_cbranch_execnz .LBB0_299
	s_or_b64 exec, exec, s[38:39]
	s_and_b64 vcc, exec, s[6:7]
	s_cbranch_vccz .LBB0_300

.LBB0_299:
	v_lshlrev_b64 v[38:39], 5, v[34:35]
	v_lshl_add_u64 v[38:39], s[72:73], 0, v[38:39]
	global_store_dwordx4 v[38:39], v[30:33], off sc1
	global_store_dwordx4 v[38:39], v[26:29], off offset:16 sc1
	s_or_b64 exec, exec, s[38:39]
	s_and_b64 vcc, exec, s[6:7]
	s_cbranch_vccnz .LBB0_298
.LBB0_300:
	v_cvt_pk_bf16_f32 v38, v22, v23
	v_cvt_pk_bf16_f32 v39, v24, v25
	v_cvt_pk_bf16_f32 v40, v18, v19
	v_cvt_pk_bf16_f32 v41, v20, v21
	global_store_dwordx4 v[36:37], v[38:41], off offset:256 sc1
	s_and_b64 vcc, exec, s[8:9]
	s_cbranch_vccnz .LBB0_304

.LBB0_304:
	s_waitcnt lgkmcnt(0)
	v_add_u32_e32 v18, 0xb0, v146
	v_mov_b64_e32 v[20:21], s[74:75]
	v_mad_i64_i32 v[20:21], s[38:39], v18, s42, v[20:21]
	v_ashrrev_i32_e32 v19, 31, v18
	v_lshl_add_u64 v[20:21], v[144:145], 1, v[20:21]
	v_cvt_pk_bf16_f32 v22, v14, v15
	v_cvt_pk_bf16_f32 v23, v16, v17
	v_cvt_pk_bf16_f32 v24, v10, v11
	v_cvt_pk_bf16_f32 v25, v12, v13
	global_store_dwordx4 v[20:21], v[22:25], off sc1
	s_and_saveexec_b64 s[38:39], s[36:37]
	s_cbranch_execnz .LBB0_310
	s_or_b64 exec, exec, s[38:39]
	s_and_b64 vcc, exec, s[6:7]
	s_cbranch_vccz .LBB0_311
